# deferred w_glu/w_out_c items re-slotted over four grid barriers (3+4+4+3) plus two at the pass C start
# baseline (speedup 1.0000x reference)
.LBB0_1103:
	s_waitcnt vmcnt(0)
	s_waitcnt lgkmcnt(0)
	s_barrier
	s_cmp_eq_u32 s97, 0x100
	s_cbranch_scc0 .Lb5_skip
	v_readlane_b32 s7, v255, 2
	v_readlane_b32 s6, v255, 7
	s_nop 0
	s_lshr_b32 s7, s7, 6
	s_cmp_eq_u32 s7, 0
	s_cbranch_scc1 .Lb5_skip
	s_cmp_gt_u32 s7, 3
	s_cbranch_scc1 .Lb5_skip
	v_writelane_b32 v206, s30, 0
	v_writelane_b32 v206, s92, 1
	v_writelane_b32 v206, exec_lo, 2
	v_writelane_b32 v206, exec_hi, 3
	s_mov_b64 exec, -1
	v_mov_b32_e32 v187, v1
	v_mov_b32_e32 v188, v5
	v_mov_b32_e32 v189, v21
	v_mov_b32_e32 v190, v24
	v_mov_b32_e32 v191, v25
	v_mov_b32_e32 v192, v26
	v_mov_b32_e32 v193, v27
	v_mov_b32_e32 v194, v30
	v_mov_b32_e32 v195, v31
	v_mov_b32_e32 v196, v34
	v_mov_b32_e32 v197, v35
	v_mov_b32_e32 v198, v47
	v_mov_b32_e32 v199, v48
	v_mov_b32_e32 v200, v49
	v_mov_b32_e32 v201, v73
	v_mov_b32_e32 v202, v86
	v_mov_b32_e32 v203, v87
	v_mov_b32_e32 v204, v104
	v_mov_b32_e32 v205, v105
	s_add_i32 s92, s7, -1
	s_lshl_b32 s92, s92, 8
	s_add_i32 s92, s92, s6
	s_add_i32 s92, s92, 0x3800
	s_mov_b64 s[100:101], s[4:5]
	s_mov_b32 s98, 1
	s_mov_b32 s99, 0x47ff
	s_movk_i32 s48, 0x1000
	v_readlane_b32 s0, v255, 3
	v_readlane_b32 s1, v255, 4
	v_readlane_b32 s2, v255, 0
	v_readlane_b32 s3, v255, 1
	v_mov_b32_e32 v163, v0
	v_and_b32_e32 v162, 63, v0
	s_lshl_b32 s30, s7, 14
	s_nop 4
	s_branch .Ltr_f3
.Lb5_ret:
	s_mov_b32 s98, 0
	s_mov_b64 s[4:5], s[100:101]
	s_mov_b64 exec, -1
	v_mov_b32_e32 v1, v187
	v_mov_b32_e32 v5, v188
	v_mov_b32_e32 v21, v189
	v_mov_b32_e32 v24, v190
	v_mov_b32_e32 v25, v191
	v_mov_b32_e32 v26, v192
	v_mov_b32_e32 v27, v193
	v_mov_b32_e32 v30, v194
	v_mov_b32_e32 v31, v195
	v_mov_b32_e32 v34, v196
	v_mov_b32_e32 v35, v197
	v_mov_b32_e32 v47, v198
	v_mov_b32_e32 v48, v199
	v_mov_b32_e32 v49, v200
	v_mov_b32_e32 v73, v201
	v_mov_b32_e32 v86, v202
	v_mov_b32_e32 v87, v203
	v_mov_b32_e32 v104, v204
	v_mov_b32_e32 v105, v205
	v_readlane_b32 s30, v206, 0
	v_readlane_b32 s92, v206, 1
	v_readlane_b32 s6, v206, 2
	v_readlane_b32 s7, v206, 3
	s_nop 1
	s_mov_b64 exec, s[6:7]

.Ltr_b3:
	s_cmp_eq_u32 s98, 6
	s_cbranch_scc1 .Lb6_ret
	s_cmp_eq_u32 s98, 1
	s_cbranch_scc1 .Lb5_ret
	s_branch .Ltr_b4

.LBB0_1256:
	s_waitcnt vmcnt(0)
	s_barrier
	s_cmp_eq_u32 s97, 0x100
	s_cbranch_scc0 .Lb6_skip
	v_readlane_b32 s7, v255, 2
	v_readlane_b32 s6, v255, 7
	s_nop 0
	s_lshr_b32 s7, s7, 6
	s_cmp_eq_u32 s7, 0
	s_cbranch_scc1 .Lb6_skip
	s_cmp_gt_u32 s7, 4
	s_cbranch_scc1 .Lb6_skip
	s_mov_b64 s[46:47], exec
	s_mov_b64 exec, -1
	s_add_i32 s92, s7, 2
	s_lshl_b32 s92, s92, 8
	s_add_i32 s92, s92, s6
	s_add_i32 s92, s92, 0x3800
	s_mov_b64 s[100:101], s[4:5]
	s_mov_b32 s98, 6
	s_mov_b32 s99, 0x47ff
	s_movk_i32 s48, 0x1000
	v_readlane_b32 s0, v255, 3
	v_readlane_b32 s1, v255, 4
	v_readlane_b32 s2, v255, 0
	v_readlane_b32 s3, v255, 1
	v_mov_b32_e32 v163, v0
	v_and_b32_e32 v162, 63, v0
	s_lshl_b32 s30, s7, 14
	s_nop 4
	s_branch .Ltr_f3

.LBB0_1334:
	s_cmp_eq_u32 s98, 4
	s_cbranch_scc1 .Lpc_back
	s_waitcnt vmcnt(0)
	s_barrier
	s_cmp_eq_u32 s97, 0x100
	s_cbranch_scc0 .Lb7_skip
	v_readlane_b32 s7, v255, 2
	v_readlane_b32 s6, v255, 7
	s_nop 0
	s_lshr_b32 s7, s7, 6
	s_cmp_eq_u32 s7, 0
	s_cbranch_scc1 .Lb7_skip
	s_cmp_gt_u32 s7, 4
	s_cbranch_scc1 .Lb7_skip
	s_mov_b64 s[46:47], exec
	s_mov_b64 exec, -1
	s_add_i32 s92, s7, 6
	s_lshl_b32 s92, s92, 8
	s_add_i32 s92, s92, s6
	s_add_i32 s92, s92, 0x3800
	s_mov_b64 s[100:101], s[4:5]
	s_mov_b32 s98, 7
	s_mov_b32 s99, 0x47ff
	s_movk_i32 s48, 0x1000
	v_readlane_b32 s0, v255, 3
	v_readlane_b32 s1, v255, 4
	v_readlane_b32 s2, v255, 0
	v_readlane_b32 s3, v255, 1
	v_mov_b32_e32 v163, v0
	v_and_b32_e32 v162, 63, v0
	s_lshl_b32 s30, s7, 14
	s_nop 4
	s_branch .Ltr_f4

.LBB0_1386:
	s_or_b64 exec, exec, s[0:1]
	v_readlane_b32 s2, v255, 3
	v_readlane_b32 s3, v255, 4
	s_waitcnt lgkmcnt(0)
	v_mov_b32_e32 v2, v0
	v_readlane_b32 s0, v255, 7
	s_barrier
	s_cmpk_gt_i32 s0, 0x3ff
	v_readfirstlane_b32 s6, v2
	s_cbranch_scc1 .LBB0_1414
	s_cmp_eq_u32 s97, 0x100
	s_cbranch_scc0 .Lpc_compiled
	v_readlane_b32 s6, v255, 7
	v_readlane_b32 s7, v255, 2
	s_nop 0
	s_lshr_b32 s7, s7, 6
	s_cmp_lt_u32 s7, 4
	s_cbranch_scc1 .Lpc_smp
	s_cmp_lt_u32 s7, 6
	s_cbranch_scc1 .Lpc_start
	s_add_i32 s7, s7, -6
	s_mov_b64 s[100:101], s[4:5]
	s_mov_b32 s98, 5
	s_mov_b32 s99, 0x47ff
	s_movk_i32 s48, 0x1000
	s_add_i32 s92, s7, 11
	s_lshl_b32 s92, s92, 8
	s_add_i32 s92, s92, s6
	s_add_i32 s92, s92, 0x3800
	v_readlane_b32 s0, v255, 3
	v_readlane_b32 s1, v255, 4
	v_readlane_b32 s2, v255, 0
	v_readlane_b32 s3, v255, 1
	v_and_b32_e32 v162, 63, v163
	s_lshl_b32 s30, s7, 14
	s_nop 4
	s_branch .Ltr_f4

.LBB0_1414:
	s_waitcnt vmcnt(0)
	s_barrier
	s_cmp_eq_u32 s97, 0x100
	s_cbranch_scc0 .Lb8_skip
	v_readlane_b32 s7, v255, 2
	v_readlane_b32 s6, v255, 7
	s_nop 0
	s_lshr_b32 s7, s7, 6
	s_cmp_eq_u32 s7, 0
	s_cbranch_scc1 .Lb8_skip
	s_cmp_gt_u32 s7, 3
	s_cbranch_scc1 .Lb8_skip
	s_mov_b64 s[46:47], exec
	s_mov_b64 exec, -1
	s_add_i32 s92, s7, 12
	s_lshl_b32 s92, s92, 8
	s_add_i32 s92, s92, s6
	s_add_i32 s92, s92, 0x3800
	s_mov_b64 s[100:101], s[4:5]
	s_mov_b32 s98, 8
	s_mov_b32 s99, 0x47ff
	s_movk_i32 s48, 0x1000
	v_readlane_b32 s0, v255, 3
	v_readlane_b32 s1, v255, 4
	v_readlane_b32 s2, v255, 0
	v_readlane_b32 s3, v255, 1
	v_mov_b32_e32 v163, v0
	v_and_b32_e32 v162, 63, v0
	s_lshl_b32 s30, s7, 14
	s_nop 4
	s_branch .Ltr_f4
